# even-layer output projection: residual epilogue hand-written (fp32 rows requested per 128-row half, write-through bf16 stores)
# speedup vs baseline: 1.0063x; 1.0063x over previous
.LBB0_762:
	v_lshl_or_b32 v144, v166, 2, s36
	v_mad_u64_u32 v[144:145], s[6:7], v167, s27, v[144:145]
	v_cvt_pk_bf16_f32 v98, v98, v99
	v_cvt_pk_bf16_f32 v99, v100, v101
	v_cvt_pk_bf16_f32 v66, v66, v67
	v_cvt_pk_bf16_f32 v58, v58, v59
	v_cvt_pk_bf16_f32 v59, v60, v61
	s_nop 0
	v_lshl_add_u32 v143, v144, 1, 0
	v_add_u32_e32 v100, 0x6000, v143
	v_add_u32_e32 v60, 0x10820, v143
	v_cvt_pk_bf16_f32 v50, v50, v51
	v_cvt_pk_bf16_f32 v51, v52, v53
	v_add_u32_e32 v52, 0x12920, v143
	v_cvt_pk_bf16_f32 v42, v42, v43
	v_cvt_pk_bf16_f32 v43, v44, v45
	v_add_u32_e32 v44, 0x14a20, v143
	v_cvt_pk_bf16_f32 v34, v34, v35
	v_cvt_pk_bf16_f32 v35, v36, v37
	v_add_u32_e32 v36, 0x16b20, v143
	v_cvt_pk_bf16_f32 v26, v26, v27
	v_cvt_pk_bf16_f32 v27, v28, v29
	v_add_u32_e32 v28, 0x10920, v143
	v_cvt_pk_bf16_f32 v18, v18, v19
	v_cvt_pk_bf16_f32 v19, v20, v21
	v_add_u32_e32 v20, 0x12a20, v143
	v_cvt_pk_bf16_f32 v10, v10, v11
	v_cvt_pk_bf16_f32 v11, v12, v13
	v_add_u32_e32 v12, 0x14b20, v143
	s_lshl_b32 s33, s29, 8
	v_cvt_pk_bf16_f32 v114, v114, v115
	v_cvt_pk_bf16_f32 v115, v116, v117
	v_add_u32_e32 v116, 0x2000, v143
	v_cvt_pk_bf16_f32 v106, v106, v107
	v_cvt_pk_bf16_f32 v107, v108, v109
	v_add_u32_e32 v108, 0x4000, v143
	v_cvt_pk_bf16_f32 v70, v70, v71
	v_cvt_pk_bf16_f32 v71, v72, v73
	v_cvt_pk_bf16_f32 v67, v68, v69
	ds_write2_b64 v100, v[70:71], v[66:67] offset0:128 offset1:132
	v_add_u32_e32 v66, 0x10800, v143
	ds_write_b64 v60, v[58:59]
	v_add_u32_e32 v58, 0x12900, v143
	ds_write_b64 v52, v[50:51]
	v_add_u32_e32 v50, 0x14a00, v143
	ds_write_b64 v44, v[42:43]
	v_add_u32_e32 v42, 0x16b00, v143
	ds_write_b64 v36, v[34:35]
	v_add_u32_e32 v34, 0x10900, v143
	ds_write_b64 v28, v[26:27]
	v_add_u32_e32 v26, 0x12a00, v143
	ds_write_b64 v20, v[18:19]
	v_add_u32_e32 v18, 0x14b00, v143
	ds_write_b64 v12, v[10:11]
	v_add_u32_e32 v10, 0x16c00, v143
	v_cvt_pk_bf16_f32 v2, v2, v3
	v_cvt_pk_bf16_f32 v3, v4, v5
	v_add_u32_e32 v4, 0x16c20, v143
	s_lshl_b32 s34, s30, 1
	s_mov_b32 s35, 0
	v_cvt_pk_bf16_f32 v126, v126, v127
	v_cvt_pk_bf16_f32 v127, v128, v129
	v_cvt_pk_bf16_f32 v122, v122, v123
	v_cvt_pk_bf16_f32 v123, v124, v125
	ds_write2_b64 v143, v[126:127], v[122:123] offset1:4
	v_cvt_pk_bf16_f32 v118, v118, v119
	v_cvt_pk_bf16_f32 v119, v120, v121
	ds_write2_b64 v116, v[118:119], v[114:115] offset0:32 offset1:36
	v_cvt_pk_bf16_f32 v110, v110, v111
	v_cvt_pk_bf16_f32 v111, v112, v113
	ds_write2_b64 v108, v[110:111], v[106:107] offset0:64 offset1:68
	v_cvt_pk_bf16_f32 v102, v102, v103
	v_cvt_pk_bf16_f32 v103, v104, v105
	ds_write2_b64 v100, v[102:103], v[98:99] offset0:96 offset1:100
	v_cvt_pk_bf16_f32 v94, v94, v95
	v_cvt_pk_bf16_f32 v95, v96, v97
	v_cvt_pk_bf16_f32 v90, v90, v91
	v_cvt_pk_bf16_f32 v91, v92, v93
	ds_write2_b64 v143, v[94:95], v[90:91] offset0:32 offset1:36
	v_cvt_pk_bf16_f32 v86, v86, v87
	v_cvt_pk_bf16_f32 v87, v88, v89
	v_cvt_pk_bf16_f32 v82, v82, v83
	v_cvt_pk_bf16_f32 v83, v84, v85
	ds_write2_b64 v116, v[86:87], v[82:83] offset0:64 offset1:68
	v_cvt_pk_bf16_f32 v78, v78, v79
	v_cvt_pk_bf16_f32 v79, v80, v81
	v_cvt_pk_bf16_f32 v74, v74, v75
	v_cvt_pk_bf16_f32 v75, v76, v77
	ds_write2_b64 v108, v[78:79], v[74:75] offset0:96 offset1:100
	v_cvt_pk_bf16_f32 v62, v62, v63
	v_cvt_pk_bf16_f32 v63, v64, v65
	ds_write_b64 v66, v[62:63]
	v_cvt_pk_bf16_f32 v54, v54, v55
	v_cvt_pk_bf16_f32 v55, v56, v57
	ds_write_b64 v58, v[54:55]
	v_cvt_pk_bf16_f32 v46, v46, v47
	v_cvt_pk_bf16_f32 v47, v48, v49
	ds_write_b64 v50, v[46:47]
	v_cvt_pk_bf16_f32 v38, v38, v39
	v_cvt_pk_bf16_f32 v39, v40, v41
	ds_write_b64 v42, v[38:39]
	v_cvt_pk_bf16_f32 v30, v30, v31
	v_cvt_pk_bf16_f32 v31, v32, v33
	ds_write_b64 v34, v[30:31]
	v_cvt_pk_bf16_f32 v22, v22, v23
	v_cvt_pk_bf16_f32 v23, v24, v25
	ds_write_b64 v26, v[22:23]
	v_cvt_pk_bf16_f32 v14, v14, v15
	v_cvt_pk_bf16_f32 v15, v16, v17
	ds_write_b64 v18, v[14:15]
	v_cvt_pk_bf16_f32 v6, v6, v7
	v_cvt_pk_bf16_f32 v7, v8, v9
	ds_write_b64 v10, v[6:7]
	ds_write_b64 v4, v[2:3]
	v_lshlrev_b32_e32 v2, 3, v0
	v_and_b32_e32 v2, 0x78, v2
	v_lshrrev_b32_e32 v3, 4, v0
	v_mul_u32_u24_e32 v4, 0x210, v3
	v_lshl_add_u32 v4, v2, 1, v4
	v_add_u32_e32 v5, 0x10800, v4
	s_add_i32 s35, s34, 0
	s_lshl_b32 s36, s35, 7
	s_add_i32 s31, s36, 0xffffe000
	s_ashr_i32 s31, s31, 10
	s_cmp_gt_i32 s35, 63
	s_cselect_b32 s31, s31, 8
	s_mul_i32 s31, s31, 0x6000
	s_add_u32 s6, s0, s31
	s_addc_u32 s7, s1, 0
	s_add_u32 s6, s6, 0xa000
	s_addc_u32 s7, s7, 0
	s_cmp_lt_i32 s36, 0x2000
	s_cselect_b32 s22, s8, s10
	s_cselect_b32 s23, s9, s11
	s_and_b32 s31, s36, 0x1fff
	v_add_u32_e32 v122, s31, v3
	v_lshlrev_b32_e32 v122, 12, v122
	v_add_u32_e32 v123, s36, v3
	v_lshlrev_b32_e32 v123, 11, v123
	s_mov_b32 s31, s33
	v_or_b32_e32 v124, s31, v2
	v_lshlrev_b32_e32 v22, 2, v124
	v_add_u32_e32 v6, v22, v122
	v_lshl_add_u32 v14, v124, 1, v123
	v_add_u32_e32 v7, 0x20000, v6
	v_add_u32_e32 v15, 0x10000, v14
	v_add_u32_e32 v8, 0x40000, v6
	v_add_u32_e32 v16, 0x20000, v14
	v_add_u32_e32 v9, 0x60000, v6
	v_add_u32_e32 v17, 0x30000, v14
	global_load_dwordx4 v[26:29], v6, s[22:23]
	global_load_dwordx4 v[30:33], v6, s[22:23] offset:16
	global_load_dwordx4 v[34:37], v7, s[22:23]
	global_load_dwordx4 v[38:41], v7, s[22:23] offset:16
	global_load_dwordx4 v[42:45], v8, s[22:23]
	global_load_dwordx4 v[46:49], v8, s[22:23] offset:16
	global_load_dwordx4 v[50:53], v9, s[22:23]
	global_load_dwordx4 v[54:57], v9, s[22:23] offset:16
	global_load_dwordx4 v[90:93], v22, s[6:7]
	global_load_dwordx4 v[94:97], v22, s[6:7] offset:16
	s_or_b32 s31, s33, 0x80
	v_or_b32_e32 v124, s31, v2
	v_lshlrev_b32_e32 v23, 2, v124
	v_add_u32_e32 v10, v23, v122
	v_lshl_add_u32 v18, v124, 1, v123
	v_add_u32_e32 v11, 0x20000, v10
	v_add_u32_e32 v19, 0x10000, v18
	v_add_u32_e32 v12, 0x40000, v10
	v_add_u32_e32 v20, 0x20000, v18
	v_add_u32_e32 v13, 0x60000, v10
	v_add_u32_e32 v21, 0x30000, v18
	global_load_dwordx4 v[58:61], v10, s[22:23]
	global_load_dwordx4 v[62:65], v10, s[22:23] offset:16
	global_load_dwordx4 v[66:69], v11, s[22:23]
	global_load_dwordx4 v[70:73], v11, s[22:23] offset:16
	global_load_dwordx4 v[74:77], v12, s[22:23]
	global_load_dwordx4 v[78:81], v12, s[22:23] offset:16
	global_load_dwordx4 v[82:85], v13, s[22:23]
	global_load_dwordx4 v[86:89], v13, s[22:23] offset:16
	global_load_dwordx4 v[98:101], v23, s[6:7]
	global_load_dwordx4 v[102:105], v23, s[6:7] offset:16
	s_waitcnt lgkmcnt(0)
	s_barrier
	s_branch .LBB0_765
.LBB0_765:
	ds_read_b128 v[172:175], v4
	ds_read_b128 v[176:179], v4 offset:16896
	ds_read_b128 v[180:183], v4 offset:33792
	ds_read_b128 v[184:187], v4 offset:50688
	s_waitcnt lgkmcnt(3)
	v_lshlrev_b32_e32 v188, 16, v172
	v_and_b32_e32 v189, 0xffff0000, v172
	v_lshlrev_b32_e32 v190, 16, v173
	v_and_b32_e32 v191, 0xffff0000, v173
	v_lshlrev_b32_e32 v192, 16, v174
	v_and_b32_e32 v193, 0xffff0000, v174
	v_lshlrev_b32_e32 v194, 16, v175
	v_and_b32_e32 v195, 0xffff0000, v175
	s_waitcnt vmcnt(10)
	v_fmac_f32_e32 v26, v90, v188
	v_fmac_f32_e32 v27, v91, v189
	v_fmac_f32_e32 v28, v92, v190
	v_fmac_f32_e32 v29, v93, v191
	v_fmac_f32_e32 v30, v94, v192
	v_fmac_f32_e32 v31, v95, v193
	v_fmac_f32_e32 v32, v96, v194
	v_fmac_f32_e32 v33, v97, v195
	v_cvt_pk_bf16_f32 v26, v26, v27
	v_cvt_pk_bf16_f32 v27, v28, v29
	v_cvt_pk_bf16_f32 v28, v30, v31
	v_cvt_pk_bf16_f32 v29, v32, v33
	global_store_dwordx4 v14, v[26:29], s[12:13] sc1
	s_waitcnt lgkmcnt(2)
	v_lshlrev_b32_e32 v188, 16, v176
	v_and_b32_e32 v189, 0xffff0000, v176
	v_lshlrev_b32_e32 v190, 16, v177
	v_and_b32_e32 v191, 0xffff0000, v177
	v_lshlrev_b32_e32 v192, 16, v178
	v_and_b32_e32 v193, 0xffff0000, v178
	v_lshlrev_b32_e32 v194, 16, v179
	v_and_b32_e32 v195, 0xffff0000, v179
	v_fmac_f32_e32 v34, v90, v188
	v_fmac_f32_e32 v35, v91, v189
	v_fmac_f32_e32 v36, v92, v190
	v_fmac_f32_e32 v37, v93, v191
	v_fmac_f32_e32 v38, v94, v192
	v_fmac_f32_e32 v39, v95, v193
	v_fmac_f32_e32 v40, v96, v194
	v_fmac_f32_e32 v41, v97, v195
	v_cvt_pk_bf16_f32 v34, v34, v35
	v_cvt_pk_bf16_f32 v35, v36, v37
	v_cvt_pk_bf16_f32 v36, v38, v39
	v_cvt_pk_bf16_f32 v37, v40, v41
	global_store_dwordx4 v15, v[34:37], s[12:13] sc1
	s_waitcnt lgkmcnt(1)
	v_lshlrev_b32_e32 v188, 16, v180
	v_and_b32_e32 v189, 0xffff0000, v180
	v_lshlrev_b32_e32 v190, 16, v181
	v_and_b32_e32 v191, 0xffff0000, v181
	v_lshlrev_b32_e32 v192, 16, v182
	v_and_b32_e32 v193, 0xffff0000, v182
	v_lshlrev_b32_e32 v194, 16, v183
	v_and_b32_e32 v195, 0xffff0000, v183
	v_fmac_f32_e32 v42, v90, v188
	v_fmac_f32_e32 v43, v91, v189
	v_fmac_f32_e32 v44, v92, v190
	v_fmac_f32_e32 v45, v93, v191
	v_fmac_f32_e32 v46, v94, v192
	v_fmac_f32_e32 v47, v95, v193
	v_fmac_f32_e32 v48, v96, v194
	v_fmac_f32_e32 v49, v97, v195
	v_cvt_pk_bf16_f32 v42, v42, v43
	v_cvt_pk_bf16_f32 v43, v44, v45
	v_cvt_pk_bf16_f32 v44, v46, v47
	v_cvt_pk_bf16_f32 v45, v48, v49
	global_store_dwordx4 v16, v[42:45], s[12:13] sc1
	s_waitcnt lgkmcnt(0)
	v_lshlrev_b32_e32 v188, 16, v184
	v_and_b32_e32 v189, 0xffff0000, v184
	v_lshlrev_b32_e32 v190, 16, v185
	v_and_b32_e32 v191, 0xffff0000, v185
	v_lshlrev_b32_e32 v192, 16, v186
	v_and_b32_e32 v193, 0xffff0000, v186
	v_lshlrev_b32_e32 v194, 16, v187
	v_and_b32_e32 v195, 0xffff0000, v187
	ds_read_b128 v[172:175], v4 offset:256
	ds_read_b128 v[176:179], v4 offset:17152
	ds_read_b128 v[180:183], v4 offset:34048
	ds_read_b128 v[184:187], v4 offset:50944
	v_fmac_f32_e32 v50, v90, v188
	v_fmac_f32_e32 v51, v91, v189
	v_fmac_f32_e32 v52, v92, v190
	v_fmac_f32_e32 v53, v93, v191
	v_fmac_f32_e32 v54, v94, v192
	v_fmac_f32_e32 v55, v95, v193
	v_fmac_f32_e32 v56, v96, v194
	v_fmac_f32_e32 v57, v97, v195
	v_cvt_pk_bf16_f32 v50, v50, v51
	v_cvt_pk_bf16_f32 v51, v52, v53
	v_cvt_pk_bf16_f32 v52, v54, v55
	v_cvt_pk_bf16_f32 v53, v56, v57
	global_store_dwordx4 v17, v[50:53], s[12:13] sc1
	s_waitcnt lgkmcnt(3)
	v_lshlrev_b32_e32 v188, 16, v172
	v_and_b32_e32 v189, 0xffff0000, v172
	v_lshlrev_b32_e32 v190, 16, v173
	v_and_b32_e32 v191, 0xffff0000, v173
	v_lshlrev_b32_e32 v192, 16, v174
	v_and_b32_e32 v193, 0xffff0000, v174
	v_lshlrev_b32_e32 v194, 16, v175
	v_and_b32_e32 v195, 0xffff0000, v175
	s_waitcnt vmcnt(4)
	v_fmac_f32_e32 v58, v98, v188
	v_fmac_f32_e32 v59, v99, v189
	v_fmac_f32_e32 v60, v100, v190
	v_fmac_f32_e32 v61, v101, v191
	v_fmac_f32_e32 v62, v102, v192
	v_fmac_f32_e32 v63, v103, v193
	v_fmac_f32_e32 v64, v104, v194
	v_fmac_f32_e32 v65, v105, v195
	v_cvt_pk_bf16_f32 v58, v58, v59
	v_cvt_pk_bf16_f32 v59, v60, v61
	v_cvt_pk_bf16_f32 v60, v62, v63
	v_cvt_pk_bf16_f32 v61, v64, v65
	global_store_dwordx4 v18, v[58:61], s[12:13] sc1
	s_waitcnt lgkmcnt(2)
	v_lshlrev_b32_e32 v188, 16, v176
	v_and_b32_e32 v189, 0xffff0000, v176
	v_lshlrev_b32_e32 v190, 16, v177
	v_and_b32_e32 v191, 0xffff0000, v177
	v_lshlrev_b32_e32 v192, 16, v178
	v_and_b32_e32 v193, 0xffff0000, v178
	v_lshlrev_b32_e32 v194, 16, v179
	v_and_b32_e32 v195, 0xffff0000, v179
	v_fmac_f32_e32 v66, v98, v188
	v_fmac_f32_e32 v67, v99, v189
	v_fmac_f32_e32 v68, v100, v190
	v_fmac_f32_e32 v69, v101, v191
	v_fmac_f32_e32 v70, v102, v192
	v_fmac_f32_e32 v71, v103, v193
	v_fmac_f32_e32 v72, v104, v194
	v_fmac_f32_e32 v73, v105, v195
	v_cvt_pk_bf16_f32 v66, v66, v67
	v_cvt_pk_bf16_f32 v67, v68, v69
	v_cvt_pk_bf16_f32 v68, v70, v71
	v_cvt_pk_bf16_f32 v69, v72, v73
	global_store_dwordx4 v19, v[66:69], s[12:13] sc1
	s_waitcnt lgkmcnt(1)
	v_lshlrev_b32_e32 v188, 16, v180
	v_and_b32_e32 v189, 0xffff0000, v180
	v_lshlrev_b32_e32 v190, 16, v181
	v_and_b32_e32 v191, 0xffff0000, v181
	v_lshlrev_b32_e32 v192, 16, v182
	v_and_b32_e32 v193, 0xffff0000, v182
	v_lshlrev_b32_e32 v194, 16, v183
	v_and_b32_e32 v195, 0xffff0000, v183
	v_fmac_f32_e32 v74, v98, v188
	v_fmac_f32_e32 v75, v99, v189
	v_fmac_f32_e32 v76, v100, v190
	v_fmac_f32_e32 v77, v101, v191
	v_fmac_f32_e32 v78, v102, v192
	v_fmac_f32_e32 v79, v103, v193
	v_fmac_f32_e32 v80, v104, v194
	v_fmac_f32_e32 v81, v105, v195
	v_cvt_pk_bf16_f32 v74, v74, v75
	v_cvt_pk_bf16_f32 v75, v76, v77
	v_cvt_pk_bf16_f32 v76, v78, v79
	v_cvt_pk_bf16_f32 v77, v80, v81
	global_store_dwordx4 v20, v[74:77], s[12:13] sc1
	s_waitcnt lgkmcnt(0)
	v_lshlrev_b32_e32 v188, 16, v184
	v_and_b32_e32 v189, 0xffff0000, v184
	v_lshlrev_b32_e32 v190, 16, v185
	v_and_b32_e32 v191, 0xffff0000, v185
	v_lshlrev_b32_e32 v192, 16, v186
	v_and_b32_e32 v193, 0xffff0000, v186
	v_lshlrev_b32_e32 v194, 16, v187
	v_and_b32_e32 v195, 0xffff0000, v187
	v_fmac_f32_e32 v82, v98, v188
	v_fmac_f32_e32 v83, v99, v189
	v_fmac_f32_e32 v84, v100, v190
	v_fmac_f32_e32 v85, v101, v191
	v_fmac_f32_e32 v86, v102, v192
	v_fmac_f32_e32 v87, v103, v193
	v_fmac_f32_e32 v88, v104, v194
	v_fmac_f32_e32 v89, v105, v195
	v_cvt_pk_bf16_f32 v82, v82, v83
	v_cvt_pk_bf16_f32 v83, v84, v85
	v_cvt_pk_bf16_f32 v84, v86, v87
	v_cvt_pk_bf16_f32 v85, v88, v89
	global_store_dwordx4 v21, v[82:85], s[12:13] sc1
	s_add_i32 s35, s34, 1
	s_lshl_b32 s36, s35, 7
	s_add_i32 s31, s36, 0xffffe000
	s_ashr_i32 s31, s31, 10
	s_cmp_gt_i32 s35, 63
	s_cselect_b32 s31, s31, 8
	s_mul_i32 s31, s31, 0x6000
	s_add_u32 s6, s0, s31
	s_addc_u32 s7, s1, 0
	s_add_u32 s6, s6, 0xa000
	s_addc_u32 s7, s7, 0
	s_cmp_lt_i32 s36, 0x2000
	s_cselect_b32 s22, s8, s10
	s_cselect_b32 s23, s9, s11
	s_and_b32 s31, s36, 0x1fff
	v_add_u32_e32 v122, s31, v3
	v_lshlrev_b32_e32 v122, 12, v122
	v_add_u32_e32 v123, s36, v3
	v_lshlrev_b32_e32 v123, 11, v123
	s_mov_b32 s31, s33
	v_or_b32_e32 v124, s31, v2
	v_lshlrev_b32_e32 v22, 2, v124
	v_add_u32_e32 v6, v22, v122
	v_lshl_add_u32 v14, v124, 1, v123
	v_add_u32_e32 v7, 0x20000, v6
	v_add_u32_e32 v15, 0x10000, v14
	v_add_u32_e32 v8, 0x40000, v6
	v_add_u32_e32 v16, 0x20000, v14
	v_add_u32_e32 v9, 0x60000, v6
	v_add_u32_e32 v17, 0x30000, v14
	global_load_dwordx4 v[26:29], v6, s[22:23]
	global_load_dwordx4 v[30:33], v6, s[22:23] offset:16
	global_load_dwordx4 v[34:37], v7, s[22:23]
	global_load_dwordx4 v[38:41], v7, s[22:23] offset:16
	global_load_dwordx4 v[42:45], v8, s[22:23]
	global_load_dwordx4 v[46:49], v8, s[22:23] offset:16
	global_load_dwordx4 v[50:53], v9, s[22:23]
	global_load_dwordx4 v[54:57], v9, s[22:23] offset:16
	global_load_dwordx4 v[90:93], v22, s[6:7]
	global_load_dwordx4 v[94:97], v22, s[6:7] offset:16
	s_or_b32 s31, s33, 0x80
	v_or_b32_e32 v124, s31, v2
	v_lshlrev_b32_e32 v23, 2, v124
	v_add_u32_e32 v10, v23, v122
	v_lshl_add_u32 v18, v124, 1, v123
	v_add_u32_e32 v11, 0x20000, v10
	v_add_u32_e32 v19, 0x10000, v18
	v_add_u32_e32 v12, 0x40000, v10
	v_add_u32_e32 v20, 0x20000, v18
	v_add_u32_e32 v13, 0x60000, v10
	v_add_u32_e32 v21, 0x30000, v18
	global_load_dwordx4 v[58:61], v10, s[22:23]
	global_load_dwordx4 v[62:65], v10, s[22:23] offset:16
	global_load_dwordx4 v[66:69], v11, s[22:23]
	global_load_dwordx4 v[70:73], v11, s[22:23] offset:16
	global_load_dwordx4 v[74:77], v12, s[22:23]
	global_load_dwordx4 v[78:81], v12, s[22:23] offset:16
	global_load_dwordx4 v[82:85], v13, s[22:23]
	global_load_dwordx4 v[86:89], v13, s[22:23] offset:16
	global_load_dwordx4 v[98:101], v23, s[6:7]
	global_load_dwordx4 v[102:105], v23, s[6:7] offset:16
	ds_read_b128 v[172:175], v5
	ds_read_b128 v[176:179], v5 offset:16896
	ds_read_b128 v[180:183], v5 offset:33792
	ds_read_b128 v[184:187], v5 offset:50688
	s_waitcnt lgkmcnt(3)
	v_lshlrev_b32_e32 v188, 16, v172
	v_and_b32_e32 v189, 0xffff0000, v172
	v_lshlrev_b32_e32 v190, 16, v173
	v_and_b32_e32 v191, 0xffff0000, v173
	v_lshlrev_b32_e32 v192, 16, v174
	v_and_b32_e32 v193, 0xffff0000, v174
	v_lshlrev_b32_e32 v194, 16, v175
	v_and_b32_e32 v195, 0xffff0000, v175
	s_waitcnt vmcnt(10)
	v_fmac_f32_e32 v26, v90, v188
	v_fmac_f32_e32 v27, v91, v189
	v_fmac_f32_e32 v28, v92, v190
	v_fmac_f32_e32 v29, v93, v191
	v_fmac_f32_e32 v30, v94, v192
	v_fmac_f32_e32 v31, v95, v193
	v_fmac_f32_e32 v32, v96, v194
	v_fmac_f32_e32 v33, v97, v195
	v_cvt_pk_bf16_f32 v26, v26, v27
	v_cvt_pk_bf16_f32 v27, v28, v29
	v_cvt_pk_bf16_f32 v28, v30, v31
	v_cvt_pk_bf16_f32 v29, v32, v33
	global_store_dwordx4 v14, v[26:29], s[12:13] sc1
	s_waitcnt lgkmcnt(2)
	v_lshlrev_b32_e32 v188, 16, v176
	v_and_b32_e32 v189, 0xffff0000, v176
	v_lshlrev_b32_e32 v190, 16, v177
	v_and_b32_e32 v191, 0xffff0000, v177
	v_lshlrev_b32_e32 v192, 16, v178
	v_and_b32_e32 v193, 0xffff0000, v178
	v_lshlrev_b32_e32 v194, 16, v179
	v_and_b32_e32 v195, 0xffff0000, v179
	v_fmac_f32_e32 v34, v90, v188
	v_fmac_f32_e32 v35, v91, v189
	v_fmac_f32_e32 v36, v92, v190
	v_fmac_f32_e32 v37, v93, v191
	v_fmac_f32_e32 v38, v94, v192
	v_fmac_f32_e32 v39, v95, v193
	v_fmac_f32_e32 v40, v96, v194
	v_fmac_f32_e32 v41, v97, v195
	v_cvt_pk_bf16_f32 v34, v34, v35
	v_cvt_pk_bf16_f32 v35, v36, v37
	v_cvt_pk_bf16_f32 v36, v38, v39
	v_cvt_pk_bf16_f32 v37, v40, v41
	global_store_dwordx4 v15, v[34:37], s[12:13] sc1
	s_waitcnt lgkmcnt(1)
	v_lshlrev_b32_e32 v188, 16, v180
	v_and_b32_e32 v189, 0xffff0000, v180
	v_lshlrev_b32_e32 v190, 16, v181
	v_and_b32_e32 v191, 0xffff0000, v181
	v_lshlrev_b32_e32 v192, 16, v182
	v_and_b32_e32 v193, 0xffff0000, v182
	v_lshlrev_b32_e32 v194, 16, v183
	v_and_b32_e32 v195, 0xffff0000, v183
	v_fmac_f32_e32 v42, v90, v188
	v_fmac_f32_e32 v43, v91, v189
	v_fmac_f32_e32 v44, v92, v190
	v_fmac_f32_e32 v45, v93, v191
	v_fmac_f32_e32 v46, v94, v192
	v_fmac_f32_e32 v47, v95, v193
	v_fmac_f32_e32 v48, v96, v194
	v_fmac_f32_e32 v49, v97, v195
	v_cvt_pk_bf16_f32 v42, v42, v43
	v_cvt_pk_bf16_f32 v43, v44, v45
	v_cvt_pk_bf16_f32 v44, v46, v47
	v_cvt_pk_bf16_f32 v45, v48, v49
	global_store_dwordx4 v16, v[42:45], s[12:13] sc1
	s_waitcnt lgkmcnt(0)
	v_lshlrev_b32_e32 v188, 16, v184
	v_and_b32_e32 v189, 0xffff0000, v184
	v_lshlrev_b32_e32 v190, 16, v185
	v_and_b32_e32 v191, 0xffff0000, v185
	v_lshlrev_b32_e32 v192, 16, v186
	v_and_b32_e32 v193, 0xffff0000, v186
	v_lshlrev_b32_e32 v194, 16, v187
	v_and_b32_e32 v195, 0xffff0000, v187
	ds_read_b128 v[172:175], v5 offset:256
	ds_read_b128 v[176:179], v5 offset:17152
	ds_read_b128 v[180:183], v5 offset:34048
	ds_read_b128 v[184:187], v5 offset:50944
	v_fmac_f32_e32 v50, v90, v188
	v_fmac_f32_e32 v51, v91, v189
	v_fmac_f32_e32 v52, v92, v190
	v_fmac_f32_e32 v53, v93, v191
	v_fmac_f32_e32 v54, v94, v192
	v_fmac_f32_e32 v55, v95, v193
	v_fmac_f32_e32 v56, v96, v194
	v_fmac_f32_e32 v57, v97, v195
	v_cvt_pk_bf16_f32 v50, v50, v51
	v_cvt_pk_bf16_f32 v51, v52, v53
	v_cvt_pk_bf16_f32 v52, v54, v55
	v_cvt_pk_bf16_f32 v53, v56, v57
	global_store_dwordx4 v17, v[50:53], s[12:13] sc1
	s_waitcnt lgkmcnt(3)
	v_lshlrev_b32_e32 v188, 16, v172
	v_and_b32_e32 v189, 0xffff0000, v172
	v_lshlrev_b32_e32 v190, 16, v173
	v_and_b32_e32 v191, 0xffff0000, v173
	v_lshlrev_b32_e32 v192, 16, v174
	v_and_b32_e32 v193, 0xffff0000, v174
	v_lshlrev_b32_e32 v194, 16, v175
	v_and_b32_e32 v195, 0xffff0000, v175
	s_waitcnt vmcnt(4)
	v_fmac_f32_e32 v58, v98, v188
	v_fmac_f32_e32 v59, v99, v189
	v_fmac_f32_e32 v60, v100, v190
	v_fmac_f32_e32 v61, v101, v191
	v_fmac_f32_e32 v62, v102, v192
	v_fmac_f32_e32 v63, v103, v193
	v_fmac_f32_e32 v64, v104, v194
	v_fmac_f32_e32 v65, v105, v195
	v_cvt_pk_bf16_f32 v58, v58, v59
	v_cvt_pk_bf16_f32 v59, v60, v61
	v_cvt_pk_bf16_f32 v60, v62, v63
	v_cvt_pk_bf16_f32 v61, v64, v65
	global_store_dwordx4 v18, v[58:61], s[12:13] sc1
	s_waitcnt lgkmcnt(2)
	v_lshlrev_b32_e32 v188, 16, v176
	v_and_b32_e32 v189, 0xffff0000, v176
	v_lshlrev_b32_e32 v190, 16, v177
	v_and_b32_e32 v191, 0xffff0000, v177
	v_lshlrev_b32_e32 v192, 16, v178
	v_and_b32_e32 v193, 0xffff0000, v178
	v_lshlrev_b32_e32 v194, 16, v179
	v_and_b32_e32 v195, 0xffff0000, v179
	v_fmac_f32_e32 v66, v98, v188
	v_fmac_f32_e32 v67, v99, v189
	v_fmac_f32_e32 v68, v100, v190
	v_fmac_f32_e32 v69, v101, v191
	v_fmac_f32_e32 v70, v102, v192
	v_fmac_f32_e32 v71, v103, v193
	v_fmac_f32_e32 v72, v104, v194
	v_fmac_f32_e32 v73, v105, v195
	v_cvt_pk_bf16_f32 v66, v66, v67
	v_cvt_pk_bf16_f32 v67, v68, v69
	v_cvt_pk_bf16_f32 v68, v70, v71
	v_cvt_pk_bf16_f32 v69, v72, v73
	global_store_dwordx4 v19, v[66:69], s[12:13] sc1
	s_waitcnt lgkmcnt(1)
	v_lshlrev_b32_e32 v188, 16, v180
	v_and_b32_e32 v189, 0xffff0000, v180
	v_lshlrev_b32_e32 v190, 16, v181
	v_and_b32_e32 v191, 0xffff0000, v181
	v_lshlrev_b32_e32 v192, 16, v182
	v_and_b32_e32 v193, 0xffff0000, v182
	v_lshlrev_b32_e32 v194, 16, v183
	v_and_b32_e32 v195, 0xffff0000, v183
	v_fmac_f32_e32 v74, v98, v188
	v_fmac_f32_e32 v75, v99, v189
	v_fmac_f32_e32 v76, v100, v190
	v_fmac_f32_e32 v77, v101, v191
	v_fmac_f32_e32 v78, v102, v192
	v_fmac_f32_e32 v79, v103, v193
	v_fmac_f32_e32 v80, v104, v194
	v_fmac_f32_e32 v81, v105, v195
	v_cvt_pk_bf16_f32 v74, v74, v75
	v_cvt_pk_bf16_f32 v75, v76, v77
	v_cvt_pk_bf16_f32 v76, v78, v79
	v_cvt_pk_bf16_f32 v77, v80, v81
	global_store_dwordx4 v20, v[74:77], s[12:13] sc1
	s_waitcnt lgkmcnt(0)
	v_lshlrev_b32_e32 v188, 16, v184
	v_and_b32_e32 v189, 0xffff0000, v184
	v_lshlrev_b32_e32 v190, 16, v185
	v_and_b32_e32 v191, 0xffff0000, v185
	v_lshlrev_b32_e32 v192, 16, v186
	v_and_b32_e32 v193, 0xffff0000, v186
	v_lshlrev_b32_e32 v194, 16, v187
	v_and_b32_e32 v195, 0xffff0000, v187
	v_fmac_f32_e32 v82, v98, v188
	v_fmac_f32_e32 v83, v99, v189
	v_fmac_f32_e32 v84, v100, v190
	v_fmac_f32_e32 v85, v101, v191
	v_fmac_f32_e32 v86, v102, v192
	v_fmac_f32_e32 v87, v103, v193
	v_fmac_f32_e32 v88, v104, v194
	v_fmac_f32_e32 v89, v105, v195
	v_cvt_pk_bf16_f32 v82, v82, v83
	v_cvt_pk_bf16_f32 v83, v84, v85
	v_cvt_pk_bf16_f32 v84, v86, v87
	v_cvt_pk_bf16_f32 v85, v88, v89
	global_store_dwordx4 v21, v[82:85], s[12:13] sc1
	s_branch .LBB0_737
